# sample rows of the first/final RMSNorm dealt evenly to all waves (loads ahead of the main loop); partial round of the weight-copy loop moved to other waves
# speedup vs baseline: 1.0557x; 1.0073x over previous
; __device__ __forceinline__ void p0_prologue(const Params& p, unsigned char* lds) {
;     const int tid = threadIdx.x, lane = tid & 63, wave = tid >> 6, G = gridDim.x;
;     const int gw = blockIdx.x * 8 + wave, NGW = G * 8;
;     unsigned char* ws = p.ws;
;     constexpr int NITEMS = (DM / 64) * (DIN / 32) + 2 * (DM / 64) * (DM / 32) + (DM / 64) * (2 * DFF / 32) + (DFF / 64) * (DM / 32) + (DPLE / 64) * (DM / 32);
;     for (int it = gw; it < NITEMS; it += 2 * NGW) {
;         const int it1 = it + NGW < NITEMS ? it + NGW : it;
;         TrItem t0, t1; tr_decode(p, it, t0); tr_decode(p, it1, t1);
;         f32x4 v0[8], v1[8], g0[2], g1[2];
;         tr_load(t0, lane, v0, g0); tr_load(t1, lane, v1, g1);
;         tr_store(t0, lane, v0, g0); tr_store(t1, lane, v1, g1);
;     }
.LBB0_19:
	s_or_b64 exec, exec, s[4:5]
	v_lshrrev_b32_e32 v0, 6, v176
	s_lshl_b32 s95, s2, 3
	v_add_u32_e32 v81, s95, v0
	s_movk_i32 s0, 0x1b00
	s_cmp_eq_u32 s66, 0x100
	s_cselect_b32 s0, 0x1300, s0
	s_lshl_b32 s94, s66, 3
	v_cmp_gt_i32_e32 vcc, s0, v81
	s_and_saveexec_b64 s[4:5], vcc
	s_cbranch_execz .LBB0_74
	s_lshl_b32 s1, s66, 4
	s_add_u32 s6, s64, 0x1a80000
	s_addc_u32 s7, s65, 0
	s_add_u32 s8, s64, 0x1880000
	s_addc_u32 s9, s65, 0
	s_add_u32 s10, s64, 0x1300000
	s_addc_u32 s11, s65, 0
	s_add_u32 s12, s64, 0x800000
	v_lshlrev_b32_e32 v1, 2, v176
	s_addc_u32 s13, s65, 0
	v_and_b32_e32 v80, 28, v1
	s_add_u32 s14, s64, 0x600000
	v_lshlrev_b32_e32 v0, 5, v0
	s_mov_b32 s18, 0x76981032
	v_and_b32_e32 v85, 56, v176
	v_mov_b32_e32 v83, 0
	s_addc_u32 s15, s65, 0
	v_lshl_add_u32 v84, s2, 8, v0
	s_lshl_b32 s3, s66, 9
	s_mov_b64 s[16:17], 0
	s_movk_i32 s30, 0x5ff
	s_movk_i32 s31, 0x7ff
	s_movk_i32 s33, 0x12ff
	s_movk_i32 s34, 0x187f
	s_movk_i32 s35, 0x1a7f
	s_movk_i32 s52, 0x60
	s_movk_i32 s53, 0xf80
	s_mov_b32 s54, 0x2aaaaaab
	s_mov_b32 s19, 0xba54
	s_movk_i32 s55, 0x800
	v_lshlrev_b32_e32 v82, 2, v80
	s_cmp_eq_u32 s66, 0x100
	s_cselect_b32 vcc_lo, 0x400, 0
	s_cselect_b32 vcc_hi, 0x7ff, -1
	v_add_u32_e32 v86, vcc_lo, v81
	v_and_b32_e32 v86, vcc_hi, v86
	v_lshlrev_b32_e32 v84, 5, v86
	s_branch .LBB0_22

; __device__ __forceinline__ void p0_prologue(const Params& p, unsigned char* lds) {
;     ...
;         const f32x4* gp = (const f32x4*)p.in[I_NMIX] + lane; f32x4 gv[4];
; #pragma unroll
;         for (int j = 0; j < 4; ++j) gv[j] = gp[64 * j];
;         bf16_t* XN = (bf16_t*)(ws + WS_XN);
;         for (int m0 = 4 * gw; m0 < MT; m0 += 4 * NGW) {
;             int mm[4]; const float* xr[4];
; #pragma unroll
;             for (int q = 0; q < 4; ++q) { mm[q] = m0 + q;
;                 xr[q] = mm[q] < MP ? p.in[I_XP] + (size_t)mm[q] * DM : p.in[I_XS] + (size_t)(mm[q] - MP) * DM; }
;             f32x4 v[4][4];
; #pragma unroll
;             for (int q = 0; q < 4; ++q)
; #pragma unroll
;                 for (int j = 0; j < 4; ++j) v[q][j] = __builtin_nontemporal_load((const f32x4*)xr[q] + lane + 64 * j);
.LBB0_74:
	s_or_b64 exec, exec, s[4:5]
	v_and_b32_e32 v206, 63, v176
	s_movk_i32 s0, 0x1080
	v_mov_b32_e32 v49, 0
	v_cmp_gt_i32_e32 vcc, s0, v81
	v_lshlrev_b32_e32 v178, 4, v206
	s_cmp_lg_u32 s66, 0x100
	s_cbranch_scc1 .Lxs_skip1
	v_readfirstlane_b32 s20, v81
	s_nop 3
	s_cmp_gt_u32 s20, 0x1ff
	s_cbranch_scc1 .Lxs_skip1
	v_readlane_b32 s22, v247, 2
	v_readlane_b32 s23, v247, 3
	v_readlane_b32 s24, v247, 12
	v_readlane_b32 s25, v247, 13
	s_lshl_b32 s21, s20, 12
	s_nop 1
	s_add_u32 s22, s22, s21
	s_addc_u32 s23, s23, 0
	global_load_dwordx4 v[104:107], v178, s[22:23] nt
	global_load_dwordx4 v[108:111], v178, s[22:23] offset:1024 nt
	global_load_dwordx4 v[112:115], v178, s[22:23] offset:2048 nt
	global_load_dwordx4 v[116:119], v178, s[22:23] offset:3072 nt
	s_nop 2
	global_load_dwordx4 v[120:123], v178, s[24:25]
	global_load_dwordx4 v[124:127], v178, s[24:25] offset:1024
	global_load_dwordx4 v[128:131], v178, s[24:25] offset:2048
	global_load_dwordx4 v[132:135], v178, s[24:25] offset:3072
.Lxs_skip1:
	s_and_saveexec_b64 s[6:7], vcc
	s_cbranch_execz .LBB0_79
	v_readlane_b32 s36, v247, 0
	v_readlane_b32 s48, v247, 12
	v_readlane_b32 s49, v247, 13
	s_nop 4
	global_load_dwordx4 v[0:3], v178, s[48:49] offset:3072
	global_load_dwordx4 v[4:7], v178, s[48:49] offset:2048
	global_load_dwordx4 v[8:11], v178, s[48:49] offset:1024
	global_load_dwordx4 v[12:15], v178, s[48:49]
	v_lshlrev_b32_e32 v50, 2, v81
	v_lshlrev_b32_e32 v48, 3, v206
	v_lshl_add_u64 v[16:17], s[64:65], 0, v[48:49]
	s_mov_b64 s[0:1], 0x96f5e00
	v_ashrrev_i32_e32 v51, 31, v50
	v_readlane_b32 s37, v247, 1
	v_lshl_add_u64 v[52:53], v[16:17], 0, s[0:1]
	v_lshlrev_b64 v[16:17], 12, v[50:51]
	v_lshl_add_u64 v[16:17], s[36:37], 0, v[16:17]
	s_mov_b64 s[0:1], 0x3000
	v_lshl_add_u64 v[56:57], v[16:17], 0, s[0:1]
	v_lshlrev_b64 v[16:17], 11, v[50:51]
	s_lshl_b32 s8, s66, 5
	v_or_b32_e32 v16, v16, v48
	v_readlane_b32 s38, v247, 2
	v_readlane_b32 s39, v247, 3
	s_ashr_i32 s9, s8, 31
	v_lshl_add_u64 v[16:17], s[64:65], 0, v[16:17]
	s_mov_b64 s[0:1], 0x96f7400
	v_or_b32_e32 v54, 1, v50
	v_mov_b32_e32 v55, v51
	s_lshl_b64 s[10:11], s[8:9], 12
	v_lshl_add_u64 v[58:59], v[16:17], 0, s[0:1]
	s_lshl_b64 s[12:13], s[8:9], 11
	s_mov_b64 s[14:15], 0
	s_movk_i32 s0, 0x3fff
	s_movk_i32 s1, 0x4000
	v_mov_b32_e32 v51, 0x358637bd
	s_mov_b32 s3, 0x800000
	s_movk_i32 s16, 0xf000
	s_movk_i32 s17, 0x41ff
	s_cmp_eq_u32 s66, 0x100
	s_cselect_b32 s17, 0x3fff, s17
	v_mov_b32_e32 v62, s39
	v_mov_b32_e32 v63, s37
	v_mov_b32_e32 v64, s38
	v_mov_b32_e32 v65, s36
	v_mov_b32_e32 v179, v49
	v_readlane_b32 s40, v247, 4
	v_readlane_b32 s41, v247, 5
	v_readlane_b32 s42, v247, 6
	v_readlane_b32 s43, v247, 7
	v_readlane_b32 s44, v247, 8
	v_readlane_b32 s45, v247, 9
	v_readlane_b32 s46, v247, 10
	v_readlane_b32 s47, v247, 11
	v_readlane_b32 s50, v247, 14
	v_readlane_b32 s51, v247, 15
	s_branch .LBB0_77

; __device__ __forceinline__ unsigned cvt_pk_bf16(float lo, float hi) { unsigned r; asm volatile("v_cvt_pk_bf16_f32 %0, %1, %2" : "=v"(r) : "v"(lo), "v"(hi)); return r; }
; __device__ __forceinline__ void p0_prologue(const Params& p, unsigned char* lds) {
;     ...
;             for (int q = 0; q < 4; ++q) { float s = 0.f;
; #pragma unroll
;                 for (int j = 0; j < 4; ++j) s += (v[q][j][0] * v[q][j][0] + v[q][j][1] * v[q][j][1]) + (v[q][j][2] * v[q][j][2] + v[q][j][3] * v[q][j][3]);
;                 const float rstd = rsqrtf(wave_sum(s) * (1.0f / DM) + EPS);
;                 u32x2* o8 = (u32x2*)(XN + (size_t)mm[q] * DM) + lane;
; #pragma unroll
;                 for (int j = 0; j < 4; ++j) { u32x2 o; o.x = cvt_pk_bf16(v[q][j][0] * rstd * gv[j][0], v[q][j][1] * rstd * gv[j][1]); o.y = cvt_pk_bf16(v[q][j][2] * rstd * gv[j][2], v[q][j][3] * rstd * gv[j][3]); __builtin_nontemporal_store(o, o8 + 64 * j); } }
;     ...
;     const size_t gt = (size_t)blockIdx.x * 512 + tid, NT = (size_t)G * 512;
;     { bf16_t* PB = (bf16_t*)(ws + WS_PB); constexpr size_t NPB = (size_t)MT * DPLE / 8;
;       for (size_t i0 = gt; i0 < NPB; i0 += 4 * NT) { f32x4 a[4], b[4]; size_t e[4];
; #pragma unroll
;           for (int q = 0; q < 4; ++q) { const size_t i = i0 + q * NT < NPB ? i0 + q * NT : i0; e[q] = i * 8; const float* s = e[q] < (size_t)MP * DPLE ? p.in[I_PP] + e[q] : p.in[I_PS] + (e[q] - (size_t)MP * DPLE);
.LBB0_79:
	s_or_b64 exec, exec, s[6:7]
	s_cmp_lg_u32 s66, 0x100
	s_cbranch_scc1 .Lxs_end
	s_cmp_gt_u32 s20, 0x1ff
	s_cbranch_scc1 .Lxs_end
	s_waitcnt vmcnt(16)
	v_mul_f32_e32 v136, v104, v104
	v_fmac_f32_e32 v136, v105, v105
	v_fmac_f32_e32 v136, v106, v106
	v_fmac_f32_e32 v136, v107, v107
	v_fmac_f32_e32 v136, v108, v108
	v_fmac_f32_e32 v136, v109, v109
	v_fmac_f32_e32 v136, v110, v110
	v_fmac_f32_e32 v136, v111, v111
	v_fmac_f32_e32 v136, v112, v112
	v_fmac_f32_e32 v136, v113, v113
	v_fmac_f32_e32 v136, v114, v114
	v_fmac_f32_e32 v136, v115, v115
	v_fmac_f32_e32 v136, v116, v116
	v_fmac_f32_e32 v136, v117, v117
	v_fmac_f32_e32 v136, v118, v118
	v_fmac_f32_e32 v136, v119, v119
	s_nop 1
	v_add_f32_dpp v136, v136, v136 quad_perm:[1,0,3,2] row_mask:0xf bank_mask:0xf bound_ctrl:1
	s_nop 1
	v_add_f32_dpp v136, v136, v136 quad_perm:[2,3,0,1] row_mask:0xf bank_mask:0xf bound_ctrl:1
	s_nop 1
	v_add_f32_dpp v136, v136, v136 row_half_mirror row_mask:0xf bank_mask:0xf bound_ctrl:1
	s_nop 1
	v_add_f32_dpp v136, v136, v136 row_mirror row_mask:0xf bank_mask:0xf bound_ctrl:1
	s_nop 1
	v_readlane_b32 s28, v136, 0
	v_readlane_b32 s29, v136, 16
	v_readlane_b32 s30, v136, 32
	v_readlane_b32 s31, v136, 48
	s_add_i32 s21, s20, 0x4000
	s_lshl_b32 s21, s21, 11
	s_add_u32 s26, s64, s21
	s_addc_u32 s27, s65, 0
	s_add_u32 s26, s26, 0x96f5e00
	s_addc_u32 s27, s27, 0
	v_mov_b32_e32 v138, s29
	v_mov_b32_e32 v139, s31
	v_add_f32_e32 v138, s28, v138
	v_add_f32_e32 v139, s30, v139
	v_add_f32_e32 v138, v138, v139
	v_mov_b32_e32 v139, 0x358637bd
	v_fmac_f32_e32 v139, 0x3a800000, v138
	v_lshlrev_b32_e32 v137, 3, v206
	v_rsq_f32_e32 v139, v139
	s_nop 0
	v_mul_f32_e32 v104, v104, v139
	v_mul_f32_e32 v105, v105, v139
	v_mul_f32_e32 v106, v106, v139
	v_mul_f32_e32 v107, v107, v139
	v_mul_f32_e32 v108, v108, v139
	v_mul_f32_e32 v109, v109, v139
	v_mul_f32_e32 v110, v110, v139
	v_mul_f32_e32 v111, v111, v139
	v_mul_f32_e32 v112, v112, v139
	v_mul_f32_e32 v113, v113, v139
	v_mul_f32_e32 v114, v114, v139
	v_mul_f32_e32 v115, v115, v139
	v_mul_f32_e32 v116, v116, v139
	v_mul_f32_e32 v117, v117, v139
	v_mul_f32_e32 v118, v118, v139
	v_mul_f32_e32 v119, v119, v139
	v_mul_f32_e32 v104, v104, v120
	v_mul_f32_e32 v105, v105, v121
	v_mul_f32_e32 v106, v106, v122
	v_mul_f32_e32 v107, v107, v123
	v_mul_f32_e32 v108, v108, v124
	v_mul_f32_e32 v109, v109, v125
	v_mul_f32_e32 v110, v110, v126
	v_mul_f32_e32 v111, v111, v127
	v_mul_f32_e32 v112, v112, v128
	v_mul_f32_e32 v113, v113, v129
	v_mul_f32_e32 v114, v114, v130
	v_mul_f32_e32 v115, v115, v131
	v_mul_f32_e32 v116, v116, v132
	v_mul_f32_e32 v117, v117, v133
	v_mul_f32_e32 v118, v118, v134
	v_mul_f32_e32 v119, v119, v135
	v_cvt_pk_bf16_f32 v104, v104, v105
	v_cvt_pk_bf16_f32 v105, v106, v107
	global_store_dwordx2 v137, v[104:105], s[26:27] nt
	v_cvt_pk_bf16_f32 v108, v108, v109
	v_cvt_pk_bf16_f32 v109, v110, v111
	global_store_dwordx2 v137, v[108:109], s[26:27] offset:512 nt
	v_cvt_pk_bf16_f32 v112, v112, v113
	v_cvt_pk_bf16_f32 v113, v114, v115
	global_store_dwordx2 v137, v[112:113], s[26:27] offset:1024 nt
	v_cvt_pk_bf16_f32 v116, v116, v117
	v_cvt_pk_bf16_f32 v117, v118, v119
	global_store_dwordx2 v137, v[116:117], s[26:27] offset:1536 nt
.Lxs_end:
	s_mov_b32 s3, 0
	s_ashr_i32 s87, s66, 31
	s_mov_b32 s86, s66
	s_lshl_b64 s[0:1], s[2:3], 9
	v_mov_b32_e32 v177, 0
	s_lshl_b64 s[4:5], s[86:87], 9
	v_lshl_add_u64 v[0:1], s[0:1], 0, v[176:177]
	s_add_u32 s52, s64, 0x1b35e00
	s_mov_b64 s[6:7], 0x84000
	s_mov_b64 s[16:17], 0x1b35e00
	s_addc_u32 s53, s65, 0
	v_cmp_gt_u64_e32 vcc, s[6:7], v[0:1]
	s_and_saveexec_b64 s[8:9], vcc
	v_readlane_b32 s36, v247, 0
	v_readlane_b32 s40, v247, 4
	v_readlane_b32 s41, v247, 5
	v_readlane_b32 s42, v247, 6
	v_readlane_b32 s43, v247, 7
	v_readlane_b32 s37, v247, 1
	v_readlane_b32 s38, v247, 2
	v_readlane_b32 s39, v247, 3
	v_readlane_b32 s44, v247, 8
	v_readlane_b32 s45, v247, 9
	v_readlane_b32 s46, v247, 10
	v_readlane_b32 s47, v247, 11
	v_readlane_b32 s48, v247, 12
	v_readlane_b32 s49, v247, 13
	v_readlane_b32 s50, v247, 14
	v_readlane_b32 s51, v247, 15
	s_cmp_eq_u32 s66, 0x100
	s_cbranch_scc1 .LBB0_82
	s_cbranch_execz .LBB0_82
	s_add_u32 s12, s42, 0xff000000
	s_addc_u32 s13, s43, -1
	s_lshl_b64 s[0:1], s[2:3], 14
	v_lshlrev_b64 v[2:3], 5, v[176:177]
	v_lshl_add_u64 v[2:3], s[0:1], 0, v[2:3]
	s_lshl_b64 s[14:15], s[86:87], 16
	s_lshl_b64 s[0:1], s[2:3], 13
	s_add_u32 s0, s64, s0
	s_addc_u32 s1, s65, s1
	s_mov_b32 s10, 0xff000000
	v_lshl_add_u64 v[4:5], v[176:177], 4, s[0:1]
	s_mov_b32 s11, -1
	v_lshl_add_u64 v[4:5], v[4:5], 0, s[16:17]
	s_lshl_b64 s[16:17], s[86:87], 15
	s_mov_b64 s[18:19], 0
	s_mov_b64 s[20:21], 0x80000
	s_mov_b64 s[22:23], 0x83fff
	v_mov_b64_e32 v[6:7], v[0:1]

; __global__ void __launch_bounds__(512, 2) hymba_fwd(Params p) {
;     ...
;     {
;         const int lane = threadIdx.x & 63, gw = bx * 8 + (threadIdx.x >> 6), NGW = G * 8;
;         const f32x4* gp = (const f32x4*)p.in[I_NFIN] + lane; f32x4 gv[4];
; #pragma unroll
;         for (int j = 0; j < 4; ++j) gv[j] = gp[64 * j];
;         const bf16_t* H3 = (const bf16_t*)(ws + WS_H3); const float* ss3 = (const float*)(ws + WS_SS3);
;         for (int m0 = 2 * gw; m0 < MT; m0 += 2 * NGW) { const int m1 = m0 + 1;
;             const float r0 = rsqrtf(ss3[m0] * (1.0f / DM) + EPS), r1 = rsqrtf(ss3[m1] * (1.0f / DM) + EPS);
;             u32x2 h0[4], h1[4];
; #pragma unroll
;             for (int j = 0; j < 4; ++j) { h0[j] = __builtin_nontemporal_load((const u32x2*)(H3 + (size_t)m0 * DM) + lane + 64 * j); h1[j] = __builtin_nontemporal_load((const u32x2*)(H3 + (size_t)m1 * DM) + lane + 64 * j); }
.LBB0_953:
	s_or_b64 exec, exec, s[4:5]
	s_waitcnt lgkmcnt(0)
	v_lshrrev_b32_e32 v0, 5, v176
	v_and_b32_e32 v0, 30, v0
	v_lshl_add_u32 v16, s2, 4, v0
	s_movk_i32 s0, 0x4200
	v_cmp_gt_i32_e32 vcc, s0, v16
	s_barrier
	s_and_saveexec_b64 s[0:1], vcc
	s_cbranch_execz .LBB0_956
	v_readlane_b32 s0, v247, 16
	v_readlane_b32 s12, v247, 28
	v_readlane_b32 s13, v247, 29
	s_nop 4
	global_load_dwordx4 v[0:3], v178, s[12:13]
	global_load_dwordx4 v[4:7], v178, s[12:13] offset:1024
	global_load_dwordx4 v[8:11], v178, s[12:13] offset:2048
	global_load_dwordx4 v[12:15], v178, s[12:13] offset:3072
	v_ashrrev_i32_e32 v17, 31, v16
	v_readlane_b32 s2, v247, 18
	v_lshlrev_b64 v[22:23], 12, v[16:17]
	v_readlane_b32 s1, v247, 17
	v_readlane_b32 s3, v247, 19
	v_readlane_b32 s14, v247, 30
	v_readlane_b32 s15, v247, 31
	s_lshl_b32 s2, s66, 4
	v_or_b32_e32 v22, v22, v178
	v_readlane_b32 s4, v247, 20
	v_readlane_b32 s5, v247, 21
	v_readlane_b32 s6, v247, 22
	v_readlane_b32 s7, v247, 23
	v_readlane_b32 s8, v247, 24
	v_readlane_b32 s9, v247, 25
	v_readlane_b32 s10, v247, 26
	v_readlane_b32 s11, v247, 27
	v_mov_b64_e32 v[18:19], 0x1b25600
	s_ashr_i32 s3, s2, 31
	v_lshlrev_b64 v[20:21], 11, v[16:17]
	v_lshl_add_u64 v[22:23], s[14:15], 0, v[22:23]
	s_mov_b64 s[0:1], 0x1000
	v_lshl_add_u64 v[18:19], v[16:17], 2, v[18:19]
	s_lshl_b64 s[4:5], s[2:3], 2
	v_lshl_or_b32 v20, v206, 3, v20
	s_lshl_b64 s[6:7], s[2:3], 11
	v_lshl_add_u64 v[22:23], v[22:23], 0, s[0:1]
	s_lshl_b64 s[8:9], s[2:3], 12
	s_mov_b64 s[10:11], 0
	s_mov_b32 s12, 0x3a800000
	s_waitcnt vmcnt(4)
	v_mov_b32_e32 v24, 0x358637bd
	s_mov_b32 s3, 0x800000
	s_mov_b32 s13, 0x4475000
	s_mov_b32 s14, 0x4476000
	s_movk_i32 s15, 0x41ff
	s_cmp_lg_u32 s66, 0x100
	s_cbranch_scc1 .Lp7s_skip1
	s_movk_i32 s15, 0x3fff
	v_readfirstlane_b32 s20, v16
	v_lshlrev_b32_e32 v108, 3, v206
	v_mov_b32_e32 v109, 0
	s_nop 1
	s_lshr_b32 s20, s20, 1
	s_lshr_b32 s21, s20, 2
	s_addk_i32 s21, 0x4000
	s_and_b32 s22, s20, 3
	s_lshl_b32 s23, s21, 11
	s_lshl_b32 s30, s22, 9
	s_add_u32 s23, s23, s30
	s_add_u32 s24, s64, s23
	s_addc_u32 s25, s65, 0
	s_add_u32 s24, s24, 0x4475e00
	s_addc_u32 s25, s25, 0
	s_lshl_b32 s23, s21, 2
	s_add_u32 s26, s64, s23
	s_addc_u32 s27, s65, 0
	s_add_u32 s26, s26, 0x1b25600
	s_addc_u32 s27, s27, 0
	v_readlane_b32 s28, v247, 28
	v_readlane_b32 s29, v247, 29
	s_lshl_b32 s23, s22, 10
	s_nop 2
	s_add_u32 s28, s28, s23
	s_addc_u32 s29, s29, 0
	global_load_dwordx2 v[100:101], v108, s[24:25] nt
	global_load_dword v102, v109, s[26:27]
	global_load_dwordx4 v[104:107], v178, s[28:29]
.Lp7s_skip1:
.LBB0_955:
	v_lshl_add_u64 v[26:27], s[64:65], 0, v[18:19]
	global_load_dwordx2 v[26:27], v[26:27], off
	v_lshl_add_u64 v[28:29], s[64:65], 0, v[20:21]
	v_add_co_u32_e32 v30, vcc, s13, v28
	v_add_u32_e32 v16, s2, v16
	s_nop 0
	v_addc_co_u32_e32 v31, vcc, 0, v29, vcc
	v_add_co_u32_e32 v28, vcc, s14, v28
	v_lshl_add_u64 v[18:19], v[18:19], 0, s[4:5]
	s_nop 0
	v_addc_co_u32_e32 v29, vcc, 0, v29, vcc
	global_load_dwordx2 v[32:33], v[30:31], off offset:3584 nt
	global_load_dwordx2 v[34:35], v[28:29], off offset:1536 nt
	global_load_dwordx2 v[36:37], v[28:29], off nt
	global_load_dwordx2 v[38:39], v[28:29], off offset:2048 nt
	global_load_dwordx2 v[40:41], v[28:29], off offset:512 nt
	global_load_dwordx2 v[42:43], v[28:29], off offset:2560 nt
	global_load_dwordx2 v[44:45], v[28:29], off offset:1024 nt
	global_load_dwordx2 v[46:47], v[28:29], off offset:3072 nt
	v_cmp_lt_i32_e32 vcc, s15, v16
	s_or_b64 s[10:11], vcc, s[10:11]
	v_lshl_add_u64 v[20:21], v[20:21], 0, s[6:7]
	s_mov_b64 s[98:99], exec
	s_andn2_b64 exec, exec, s[10:11]
	s_cbranch_execz .Lp7_single
	v_lshl_add_u64 v[70:71], s[64:65], 0, v[18:19]
	global_load_dwordx2 v[70:71], v[70:71], off
	v_lshl_add_u64 v[88:89], s[64:65], 0, v[20:21]
	v_add_co_u32_e32 v90, vcc, s13, v88
	v_add_u32_e32 v16, s2, v16
	s_nop 0
	v_addc_co_u32_e32 v91, vcc, 0, v89, vcc
	v_add_co_u32_e32 v88, vcc, s14, v88
	v_lshl_add_u64 v[18:19], v[18:19], 0, s[4:5]
	s_nop 0
	v_addc_co_u32_e32 v89, vcc, 0, v89, vcc
	global_load_dwordx2 v[72:73], v[90:91], off offset:3584 nt
	global_load_dwordx2 v[74:75], v[88:89], off offset:1536 nt
	global_load_dwordx2 v[76:77], v[88:89], off nt
	global_load_dwordx2 v[78:79], v[88:89], off offset:2048 nt
	global_load_dwordx2 v[80:81], v[88:89], off offset:512 nt
	global_load_dwordx2 v[82:83], v[88:89], off offset:2560 nt
	global_load_dwordx2 v[84:85], v[88:89], off offset:1024 nt
	global_load_dwordx2 v[86:87], v[88:89], off offset:3072 nt
	v_cmp_lt_i32_e32 vcc, s15, v16
	s_or_b64 s[10:11], vcc, s[10:11]
	v_lshl_add_u64 v[20:21], v[20:21], 0, s[6:7]
	s_mov_b64 s[100:101], exec
	s_mov_b64 exec, s[98:99]
	s_waitcnt vmcnt(17)
	v_pk_fma_f32 v[26:27], v[26:27], s[12:13], v[24:25] op_sel_hi:[1,0,0]
	s_nop 0
	v_mul_f32_e32 v17, 0x4b800000, v26
	v_cmp_gt_f32_e64 s[0:1], s3, v26
	v_mul_f32_e32 v25, 0x4b800000, v27
	v_cmp_gt_f32_e32 vcc, s3, v27
	v_cndmask_b32_e64 v17, v26, v17, s[0:1]
	v_rsq_f32_e32 v17, v17
	v_cndmask_b32_e32 v25, v27, v25, vcc
	v_rsq_f32_e32 v25, v25
	s_waitcnt vmcnt(16)
	v_lshlrev_b32_e32 v28, 16, v32
	v_mul_f32_e32 v26, 0x45800000, v17
	v_and_b32_e32 v29, 0xffff0000, v32
	v_lshlrev_b32_e32 v30, 16, v33
	v_and_b32_e32 v31, 0xffff0000, v33
	v_mul_f32_e32 v27, 0x45800000, v25
	v_cndmask_b32_e64 v26, v17, v26, s[0:1]
	s_waitcnt vmcnt(15)
	v_lshlrev_b32_e32 v32, 16, v34
	v_and_b32_e32 v33, 0xffff0000, v34
	v_lshlrev_b32_e32 v34, 16, v35
	v_and_b32_e32 v35, 0xffff0000, v35
	s_waitcnt vmcnt(14)
	v_lshlrev_b32_e32 v48, 16, v36
	v_and_b32_e32 v49, 0xffff0000, v36
	v_lshlrev_b32_e32 v36, 16, v37
	v_and_b32_e32 v37, 0xffff0000, v37
	s_waitcnt vmcnt(13)
; __device__ __forceinline__ f32x4 unpack4(const u32x2& w) { f32x4 a; a[0] = __uint_as_float(w.x << 16); a[1] = __uint_as_float(w.x & 0xffff0000u); a[2] = __uint_as_float(w.y << 16); a[3] = __uint_as_float(w.y & 0xffff0000u); return a; }
; __global__ void __launch_bounds__(512, 2) hymba_fwd(Params p) {
;     ...
;             const float r0 = rsqrtf(ss3[m0] * (1.0f / DM) + EPS), r1 = rsqrtf(ss3[m1] * (1.0f / DM) + EPS);
;             u32x2 h0[4], h1[4];
; #pragma unroll
;             for (int j = 0; j < 4; ++j) { h0[j] = __builtin_nontemporal_load((const u32x2*)(H3 + (size_t)m0 * DM) + lane + 64 * j); h1[j] = __builtin_nontemporal_load((const u32x2*)(H3 + (size_t)m1 * DM) + lane + 64 * j); }
; #pragma unroll
;             for (int j = 0; j < 4; ++j) { __builtin_nontemporal_store(unpack4(h0[j]) * r0 * gv[j], (f32x4*)(p.out + (size_t)m0 * DM) + lane + 64 * j); __builtin_nontemporal_store(unpack4(h1[j]) * r1 * gv[j], (f32x4*)(p.out + (size_t)m1 * DM) + lane + 64 * j); } }
	v_lshlrev_b32_e32 v50, 16, v38
	v_and_b32_e32 v51, 0xffff0000, v38
	v_lshlrev_b32_e32 v38, 16, v39
	v_and_b32_e32 v39, 0xffff0000, v39
	s_waitcnt vmcnt(12)
	v_lshlrev_b32_e32 v52, 16, v40
	v_and_b32_e32 v53, 0xffff0000, v40
	v_lshlrev_b32_e32 v40, 16, v41
	v_and_b32_e32 v41, 0xffff0000, v41
	s_waitcnt vmcnt(11)
	v_lshlrev_b32_e32 v54, 16, v42
	v_and_b32_e32 v55, 0xffff0000, v42
	v_lshlrev_b32_e32 v42, 16, v43
	v_and_b32_e32 v43, 0xffff0000, v43
	s_waitcnt vmcnt(10)
	v_lshlrev_b32_e32 v56, 16, v44
	v_and_b32_e32 v57, 0xffff0000, v44
	v_lshlrev_b32_e32 v44, 16, v45
	v_and_b32_e32 v45, 0xffff0000, v45
	s_waitcnt vmcnt(9)
	v_lshlrev_b32_e32 v58, 16, v46
	v_and_b32_e32 v59, 0xffff0000, v46
	v_lshlrev_b32_e32 v46, 16, v47
	v_and_b32_e32 v47, 0xffff0000, v47
	v_cndmask_b32_e32 v60, v25, v27, vcc
	v_pk_mul_f32 v[62:63], v[26:27], v[28:29] op_sel_hi:[0,1]
	v_pk_mul_f32 v[28:29], v[26:27], v[30:31] op_sel_hi:[0,1]
	v_pk_mul_f32 v[30:31], v[60:61], v[32:33] op_sel_hi:[0,1]
	v_pk_mul_f32 v[32:33], v[60:61], v[34:35] op_sel_hi:[0,1]
	v_pk_mul_f32 v[34:35], v[26:27], v[48:49] op_sel_hi:[0,1]
	v_pk_mul_f32 v[36:37], v[26:27], v[36:37] op_sel_hi:[0,1]
	v_pk_mul_f32 v[48:49], v[60:61], v[50:51] op_sel_hi:[0,1]
	v_pk_mul_f32 v[38:39], v[60:61], v[38:39] op_sel_hi:[0,1]
	v_pk_mul_f32 v[50:51], v[26:27], v[52:53] op_sel_hi:[0,1]
	v_pk_mul_f32 v[52:53], v[26:27], v[40:41] op_sel_hi:[0,1]
	v_pk_mul_f32 v[54:55], v[60:61], v[54:55] op_sel_hi:[0,1]
	v_pk_mul_f32 v[64:65], v[60:61], v[42:43] op_sel_hi:[0,1]
	v_pk_mul_f32 v[56:57], v[26:27], v[56:57] op_sel_hi:[0,1]
	v_pk_mul_f32 v[66:67], v[26:27], v[44:45] op_sel_hi:[0,1]
	v_pk_mul_f32 v[58:59], v[60:61], v[58:59] op_sel_hi:[0,1]
	v_pk_mul_f32 v[60:61], v[60:61], v[46:47] op_sel_hi:[0,1]
	v_pk_mul_f32 v[28:29], v[2:3], v[28:29]
	v_pk_mul_f32 v[26:27], v[0:1], v[62:63]
	v_pk_mul_f32 v[32:33], v[2:3], v[32:33]
	v_pk_mul_f32 v[30:31], v[0:1], v[30:31]
	v_pk_mul_f32 v[36:37], v[6:7], v[36:37]
	v_pk_mul_f32 v[34:35], v[4:5], v[34:35]
	v_pk_mul_f32 v[40:41], v[6:7], v[38:39]
	v_pk_mul_f32 v[38:39], v[4:5], v[48:49]
	v_pk_mul_f32 v[44:45], v[10:11], v[52:53]
	v_pk_mul_f32 v[42:43], v[8:9], v[50:51]
	v_pk_mul_f32 v[48:49], v[10:11], v[64:65]
	v_pk_mul_f32 v[46:47], v[8:9], v[54:55]
	v_pk_mul_f32 v[52:53], v[14:15], v[66:67]
	v_pk_mul_f32 v[50:51], v[12:13], v[56:57]
	v_pk_mul_f32 v[56:57], v[14:15], v[60:61]
	v_pk_mul_f32 v[54:55], v[12:13], v[58:59]
	global_store_dwordx4 v[22:23], v[26:29], off offset:-4096 nt
	global_store_dwordx4 v[22:23], v[30:33], off nt
	global_store_dwordx4 v[22:23], v[34:37], off offset:-3072 nt
	global_store_dwordx4 v[22:23], v[38:41], off offset:1024 nt
	global_store_dwordx4 v[22:23], v[42:45], off offset:-2048 nt
	global_store_dwordx4 v[22:23], v[46:49], off offset:2048 nt
	global_store_dwordx4 v[22:23], v[50:53], off offset:-1024 nt
	global_store_dwordx4 v[22:23], v[54:57], off offset:3072 nt
	v_lshl_add_u64 v[22:23], v[22:23], 0, s[8:9]
	s_mov_b64 exec, s[100:101]
	s_waitcnt vmcnt(8)
; __device__ __forceinline__ f32x4 unpack4(const u32x2& w) { f32x4 a; a[0] = __uint_as_float(w.x << 16); a[1] = __uint_as_float(w.x & 0xffff0000u); a[2] = __uint_as_float(w.y << 16); a[3] = __uint_as_float(w.y & 0xffff0000u); return a; }
; __global__ void __launch_bounds__(512, 2) hymba_fwd(Params p) {
;     ...
;         for (int m0 = 2 * gw; m0 < MT; m0 += 2 * NGW) { const int m1 = m0 + 1;
;             const float r0 = rsqrtf(ss3[m0] * (1.0f / DM) + EPS), r1 = rsqrtf(ss3[m1] * (1.0f / DM) + EPS);
;             u32x2 h0[4], h1[4];
; #pragma unroll
;             for (int j = 0; j < 4; ++j) { h0[j] = __builtin_nontemporal_load((const u32x2*)(H3 + (size_t)m0 * DM) + lane + 64 * j); h1[j] = __builtin_nontemporal_load((const u32x2*)(H3 + (size_t)m1 * DM) + lane + 64 * j); }
; #pragma unroll
;             for (int j = 0; j < 4; ++j) { __builtin_nontemporal_store(unpack4(h0[j]) * r0 * gv[j], (f32x4*)(p.out + (size_t)m0 * DM) + lane + 64 * j); __builtin_nontemporal_store(unpack4(h1[j]) * r1 * gv[j], (f32x4*)(p.out + (size_t)m1 * DM) + lane + 64 * j); } }
	v_mov_b32_e32 v26, v70
	v_mov_b32_e32 v27, v71
	v_mov_b32_e32 v32, v72
	v_mov_b32_e32 v33, v73
	v_mov_b32_e32 v34, v74
	v_mov_b32_e32 v35, v75
	v_mov_b32_e32 v36, v76
	v_mov_b32_e32 v37, v77
	v_mov_b32_e32 v38, v78
	v_mov_b32_e32 v39, v79
	v_mov_b32_e32 v40, v80
	v_mov_b32_e32 v41, v81
	v_mov_b32_e32 v42, v82
	v_mov_b32_e32 v43, v83
	v_mov_b32_e32 v44, v84
	v_mov_b32_e32 v45, v85
	v_mov_b32_e32 v46, v86
	v_mov_b32_e32 v47, v87
	v_pk_fma_f32 v[26:27], v[26:27], s[12:13], v[24:25] op_sel_hi:[1,0,0]
	s_nop 0
	v_mul_f32_e32 v17, 0x4b800000, v26
	v_cmp_gt_f32_e64 s[0:1], s3, v26
	v_mul_f32_e32 v25, 0x4b800000, v27
	v_cmp_gt_f32_e32 vcc, s3, v27
	v_cndmask_b32_e64 v17, v26, v17, s[0:1]
	v_rsq_f32_e32 v17, v17
	v_cndmask_b32_e32 v25, v27, v25, vcc
	v_rsq_f32_e32 v25, v25
	v_lshlrev_b32_e32 v28, 16, v32
	v_mul_f32_e32 v26, 0x45800000, v17
	v_and_b32_e32 v29, 0xffff0000, v32
	v_lshlrev_b32_e32 v30, 16, v33
	v_and_b32_e32 v31, 0xffff0000, v33
	v_mul_f32_e32 v27, 0x45800000, v25
	v_cndmask_b32_e64 v26, v17, v26, s[0:1]
	v_lshlrev_b32_e32 v32, 16, v34
	v_and_b32_e32 v33, 0xffff0000, v34
	v_lshlrev_b32_e32 v34, 16, v35
	v_and_b32_e32 v35, 0xffff0000, v35
	v_lshlrev_b32_e32 v48, 16, v36
	v_and_b32_e32 v49, 0xffff0000, v36
	v_lshlrev_b32_e32 v36, 16, v37
	v_and_b32_e32 v37, 0xffff0000, v37
	v_lshlrev_b32_e32 v50, 16, v38
	v_and_b32_e32 v51, 0xffff0000, v38
	v_lshlrev_b32_e32 v38, 16, v39
	v_and_b32_e32 v39, 0xffff0000, v39
	v_lshlrev_b32_e32 v52, 16, v40
	v_and_b32_e32 v53, 0xffff0000, v40
	v_lshlrev_b32_e32 v40, 16, v41
	v_and_b32_e32 v41, 0xffff0000, v41
	v_lshlrev_b32_e32 v54, 16, v42
	v_and_b32_e32 v55, 0xffff0000, v42
	v_lshlrev_b32_e32 v42, 16, v43
	v_and_b32_e32 v43, 0xffff0000, v43
	v_lshlrev_b32_e32 v56, 16, v44
	v_and_b32_e32 v57, 0xffff0000, v44
	v_lshlrev_b32_e32 v44, 16, v45
	v_and_b32_e32 v45, 0xffff0000, v45
	v_lshlrev_b32_e32 v58, 16, v46
	v_and_b32_e32 v59, 0xffff0000, v46
	v_lshlrev_b32_e32 v46, 16, v47
	v_and_b32_e32 v47, 0xffff0000, v47
	v_cndmask_b32_e32 v60, v25, v27, vcc
	v_pk_mul_f32 v[62:63], v[26:27], v[28:29] op_sel_hi:[0,1]
	v_pk_mul_f32 v[28:29], v[26:27], v[30:31] op_sel_hi:[0,1]
	v_pk_mul_f32 v[30:31], v[60:61], v[32:33] op_sel_hi:[0,1]
	v_pk_mul_f32 v[32:33], v[60:61], v[34:35] op_sel_hi:[0,1]
	v_pk_mul_f32 v[34:35], v[26:27], v[48:49] op_sel_hi:[0,1]
	v_pk_mul_f32 v[36:37], v[26:27], v[36:37] op_sel_hi:[0,1]
	v_pk_mul_f32 v[48:49], v[60:61], v[50:51] op_sel_hi:[0,1]
	v_pk_mul_f32 v[38:39], v[60:61], v[38:39] op_sel_hi:[0,1]
	v_pk_mul_f32 v[50:51], v[26:27], v[52:53] op_sel_hi:[0,1]
	v_pk_mul_f32 v[52:53], v[26:27], v[40:41] op_sel_hi:[0,1]
	v_pk_mul_f32 v[54:55], v[60:61], v[54:55] op_sel_hi:[0,1]
	v_pk_mul_f32 v[64:65], v[60:61], v[42:43] op_sel_hi:[0,1]
	v_pk_mul_f32 v[56:57], v[26:27], v[56:57] op_sel_hi:[0,1]
	v_pk_mul_f32 v[66:67], v[26:27], v[44:45] op_sel_hi:[0,1]
	v_pk_mul_f32 v[58:59], v[60:61], v[58:59] op_sel_hi:[0,1]
	v_pk_mul_f32 v[60:61], v[60:61], v[46:47] op_sel_hi:[0,1]
	v_pk_mul_f32 v[28:29], v[2:3], v[28:29]
	v_pk_mul_f32 v[26:27], v[0:1], v[62:63]
	v_pk_mul_f32 v[32:33], v[2:3], v[32:33]
	v_pk_mul_f32 v[30:31], v[0:1], v[30:31]
	v_pk_mul_f32 v[36:37], v[6:7], v[36:37]
	v_pk_mul_f32 v[34:35], v[4:5], v[34:35]
	v_pk_mul_f32 v[40:41], v[6:7], v[38:39]
	v_pk_mul_f32 v[38:39], v[4:5], v[48:49]
	v_pk_mul_f32 v[44:45], v[10:11], v[52:53]
	v_pk_mul_f32 v[42:43], v[8:9], v[50:51]
	v_pk_mul_f32 v[48:49], v[10:11], v[64:65]
	v_pk_mul_f32 v[46:47], v[8:9], v[54:55]
	v_pk_mul_f32 v[52:53], v[14:15], v[66:67]
	v_pk_mul_f32 v[50:51], v[12:13], v[56:57]
	v_pk_mul_f32 v[56:57], v[14:15], v[60:61]
	v_pk_mul_f32 v[54:55], v[12:13], v[58:59]
	global_store_dwordx4 v[22:23], v[26:29], off offset:-4096 nt
	global_store_dwordx4 v[22:23], v[30:33], off nt
	global_store_dwordx4 v[22:23], v[34:37], off offset:-3072 nt
	global_store_dwordx4 v[22:23], v[38:41], off offset:1024 nt
	global_store_dwordx4 v[22:23], v[42:45], off offset:-2048 nt
	global_store_dwordx4 v[22:23], v[46:49], off offset:2048 nt
	global_store_dwordx4 v[22:23], v[50:53], off offset:-1024 nt
	global_store_dwordx4 v[22:23], v[54:57], off offset:3072 nt
	v_lshl_add_u64 v[22:23], v[22:23], 0, s[8:9]
	s_andn2_b64 exec, exec, s[10:11]
	s_cbranch_execnz .LBB0_955
	s_branch .LBB0_956

; __device__ __forceinline__ f32x4 unpack4(const u32x2& w) { f32x4 a; a[0] = __uint_as_float(w.x << 16); a[1] = __uint_as_float(w.x & 0xffff0000u); a[2] = __uint_as_float(w.y << 16); a[3] = __uint_as_float(w.y & 0xffff0000u); return a; }
; __global__ void __launch_bounds__(512, 2) hymba_fwd(Params p) {
;     ...
;         for (int m0 = 2 * gw; m0 < MT; m0 += 2 * NGW) { const int m1 = m0 + 1;
;             const float r0 = rsqrtf(ss3[m0] * (1.0f / DM) + EPS), r1 = rsqrtf(ss3[m1] * (1.0f / DM) + EPS);
;             u32x2 h0[4], h1[4];
; #pragma unroll
;             for (int j = 0; j < 4; ++j) { h0[j] = __builtin_nontemporal_load((const u32x2*)(H3 + (size_t)m0 * DM) + lane + 64 * j); h1[j] = __builtin_nontemporal_load((const u32x2*)(H3 + (size_t)m1 * DM) + lane + 64 * j); }
; #pragma unroll
;             for (int j = 0; j < 4; ++j) { __builtin_nontemporal_store(unpack4(h0[j]) * r0 * gv[j], (f32x4*)(p.out + (size_t)m0 * DM) + lane + 64 * j); __builtin_nontemporal_store(unpack4(h1[j]) * r1 * gv[j], (f32x4*)(p.out + (size_t)m1 * DM) + lane + 64 * j); } }
.LBB0_956:
	s_mov_b64 exec, -1
	s_cmp_lg_u32 s66, 0x100
	s_cbranch_scc1 .Lp7s_end
	s_waitcnt vmcnt(16)
	v_mov_b32_e32 v103, 0x358637bd
	v_fmac_f32_e32 v103, 0x3a800000, v102
	v_lshlrev_b32_e32 v110, 16, v100
	v_and_b32_e32 v111, 0xffff0000, v100
	v_rsq_f32_e32 v103, v103
	v_lshlrev_b32_e32 v112, 16, v101
	v_and_b32_e32 v113, 0xffff0000, v101
	v_readlane_b32 s24, v247, 30
	v_readlane_b32 s25, v247, 31
	v_mul_f32_e32 v110, v103, v110
	v_mul_f32_e32 v111, v103, v111
	v_mul_f32_e32 v112, v103, v112
	v_mul_f32_e32 v113, v103, v113
	v_mul_f32_e32 v110, v104, v110
	v_mul_f32_e32 v111, v105, v111
	v_mul_f32_e32 v112, v106, v112
	v_mul_f32_e32 v113, v107, v113
	s_lshl_b32 s23, s21, 12
	s_lshl_b32 s30, s22, 10
	s_add_u32 s23, s23, s30
	s_add_u32 s24, s24, s23
	s_addc_u32 s25, s25, 0
	global_store_dwordx4 v178, v[110:113], s[24:25] nt
